# token-mixer output phase reordered: rwkv output pass runs before the four per-head value up-projection GEMMs, so the GEMM output is still cache-resident for the RMS-norm pass that follows
# speedup vs baseline: 1.0115x; 1.0011x over previous
; __global__ void __launch_bounds__(512) fwd_megakernel(Params p) {
;     ...
;       xcd_barrier(xb);
;       {
;         const u16* OP = (const u16*)(p.ws + WS_OP); u16* OO = (u16*)(p.ws + WS_OO);
;         for (int h = 0; h < 4; ++h) {
;           gemm_small(OP + h * 128, 512, (const u16*)(p.ws + WS_WUKV) + (size_t)l * 1024 * 128 + (size_t)(h * 256 + 128) * 128, 128, 128, 128, OO + h * 128, 512,
;                      [=](int n, f32x4 v) { return v; }, smem, rot);
;         }
;         rwkv_out_phase(p, l);
.LBB0_439:
	s_or_b64 exec, exec, s[0:1]
	s_mov_b32 s0, 0
	v_writelane_b32 v236, s0, 41
	s_lshl_b32 s0, s79, 18
	s_add_u32 s4, s54, s0
	s_addc_u32 s5, s55, 0
	s_mov_b32 s26, 0
	s_mov_b32 s28, 0
	s_waitcnt lgkmcnt(0)
	s_barrier
	s_branch .LBB0_462

; __device__ __forceinline__ void xcd_barrier(const XcdBarrier& b) {
;     asm volatile("s_waitcnt vmcnt(0)" ::: "memory");
;     __syncthreads();
;     if (threadIdx.x == 0) {
;         unsigned* bar = b.bar;
;         __builtin_amdgcn_s_waitcnt(0);
;         unsigned nloc = b.st[0], nx = b.st[1];
;         if (nloc == 0u) { xcd_barrier_complete(bar, b.x, nloc, nx); b.st[0] = nloc; b.st[1] = nx; }
; __global__ void __launch_bounds__(512) fwd_megakernel(Params p) {
;     ...
;         for (int h = 0; h < 4; ++h) {
;           gemm_small(OP + h * 128, 512, (const u16*)(p.ws + WS_WUKV) + (size_t)l * 1024 * 128 + (size_t)(h * 256 + 128) * 128, 128, 128, 128, OO + h * 128, 512,
;                      [=](int n, f32x4 v) { return v; }, smem, rot);
;         }
;         rwkv_out_phase(p, l);
;       }
;       xcd_barrier(xb);
.LBB0_513:
	s_or_b64 exec, exec, s[20:21]
	v_readlane_b32 s0, v236, 41
	s_cmp_eq_u32 s0, 0
	s_cbranch_scc0 .Lp6_after
	s_mov_b32 s0, 1
	v_writelane_b32 v236, s0, 41
	s_lshl_b32 s0, s79, 18
	s_add_u32 s4, s54, s0
	s_addc_u32 s5, s55, 0
	s_mov_b32 s26, 0
	s_mov_b32 s28, 0
	s_branch .LBB0_441
.Lp6_after2:
	s_movk_i32 s26, 0x1fff
.Lp6_after:
	s_waitcnt vmcnt(0)
	s_barrier
	s_and_saveexec_b64 s[0:1], s[80:81]
	v_readlane_b32 s88, v237, 52
	v_readlane_b32 s89, v237, 53
	v_readlane_b32 s90, v237, 54
	v_readlane_b32 s91, v237, 55
	v_readlane_b32 s92, v237, 56
	s_cbranch_execz .LBB0_565
	v_readlane_b32 s4, v237, 47
	s_waitcnt vmcnt(0) expcnt(0) lgkmcnt(0)
	s_nop 0
	v_mov_b32_e32 v1, s4
	ds_read_b32 v3, v1
	v_readlane_b32 s4, v237, 48
	s_waitcnt lgkmcnt(0)
	v_cmp_ne_u32_e32 vcc, 0, v3
	v_mov_b32_e32 v1, s4
	ds_read_b32 v2, v1
	s_cbranch_vccnz .LBB0_529
	s_mov_b32 s4, 1
	s_branch .LBB0_517
